# P2 residual epilogue: all 32 base-tile loads batched 16 ahead into spare VGPRs with counted vmcnt instead of load-wait-store chain
# speedup vs baseline: 1.0149x; 1.0081x over previous
; __device__ __forceinline__ unsigned pk2(float lo, float hi) { f32x2_t v = {lo, hi}; bf16x2_t b = __builtin_convertvector(v, bf16x2_t); return __builtin_bit_cast(unsigned, b); }
; __device__ __forceinline__ float xor16_sum(float v) { float a = v, b = v; swap16(a, b); return a + b; }
; __device__ __forceinline__ float xor32_sum(float v) { float a = v, b = v; swap32(a, b); return a + b; }
;     __device__ __forceinline__ void operator()(const f32x4 (&acc)[2][2][4][2], const Unit& u, int wr, int wc, int fr, int fq) const {
;         const int row0 = u.pm * BM + wr * 64 + fr; constexpr int ldc = 2048; constexpr float alpha = 0.5f * ALPHA2;
;         bf16_t* const xb = (bf16_t*)(ws + XBOFF); __attribute__((address_space(1))) float* const ss = (__attribute__((address_space(1))) float*)(ws + SSOFF);
; #pragma unroll
;         for (int ai = 0; ai < 2; ++ai)
; #pragma unroll
;             for (int m = 0; m < 4; ++m) {
;                 const int row = row0 + ai * HALF + m * 16; float sq = 0.f;
; #pragma unroll
;                 for (int bj = 0; bj < 2; ++bj)
; #pragma unroll
;                     for (int n = 0; n < 2; ++n) {
;                         const size_t idx = (size_t)row * ldc + u.pn * BM + bj * HALF + wc * 32 + 8 * fq + 4 * n;
;                         const f32x4 b = *(const f32x4*)(base + idx);
;                         const f32x4 v = b + acc[ai][bj][m][n] * alpha;
;                         *(f32x4*)(out + idx) = v;
;                         if (NORM) { u32x2 w; w.x = pk2(v[0], v[1]); w.y = pk2(v[2], v[3]); *(u32x2*)(xb + idx) = w; sq += (v[0] * v[0] + v[1] * v[1]) + (v[2] * v[2] + v[3] * v[3]); }
;                     }
;                 if (NORM) { sq = xor16_sum(sq); sq = xor32_sum(sq); if (fq == 0) __hip_atomic_fetch_add(ss + row, sq, __ATOMIC_RELAXED, __HIP_MEMORY_SCOPE_AGENT); }
.LBB0_423:
	v_lshl_add_u32 v148, s14, 8, v137
	s_lshl_b32 s12, s16, 8
	s_ashr_i32 s13, s12, 31
	v_ashrrev_i32_e32 v149, 31, v148
	v_mov_b32_e32 v147, s13
	v_or_b32_e32 v146, s12, v136
	v_lshlrev_b64 v[154:155], 11, v[148:149]
	v_lshl_add_u64 v[158:159], v[154:155], 0, v[146:147]
	v_lshlrev_b64 v[160:161], 2, v[158:159]
	v_lshl_add_u64 v[162:163], s[52:53], 0, v[160:161]
	v_mov_b32_e32 v232, v162
	v_mov_b32_e32 v233, v163
	v_mov_b32_e32 v231, 0
	v_mov_b32_e32 v230, 0x0
	v_lshl_add_u64 v[228:229], v[232:233], 0, v[230:231]
	global_load_dwordx4 v[164:167], v[228:229], off
	global_load_dwordx4 v[168:171], v[228:229], off offset:16
	global_load_dwordx4 v[172:175], v[228:229], off offset:512
	global_load_dwordx4 v[176:179], v[228:229], off offset:528
	v_mov_b32_e32 v230, 0x20000
	v_lshl_add_u64 v[228:229], v[232:233], 0, v[230:231]
	global_load_dwordx4 v[180:183], v[228:229], off
	global_load_dwordx4 v[188:191], v[228:229], off offset:16
	global_load_dwordx4 v[192:195], v[228:229], off offset:512
	global_load_dwordx4 v[196:199], v[228:229], off offset:528
	v_mov_b32_e32 v230, 0x40000
	v_lshl_add_u64 v[228:229], v[232:233], 0, v[230:231]
	global_load_dwordx4 v[200:203], v[228:229], off
	global_load_dwordx4 v[204:207], v[228:229], off offset:16
	global_load_dwordx4 v[208:211], v[228:229], off offset:512
	global_load_dwordx4 v[212:215], v[228:229], off offset:528
	v_mov_b32_e32 v230, 0x60000
	v_lshl_add_u64 v[228:229], v[232:233], 0, v[230:231]
	global_load_dwordx4 v[216:219], v[228:229], off
	global_load_dwordx4 v[220:223], v[228:229], off offset:16
	global_load_dwordx4 v[224:227], v[228:229], off offset:512
	global_load_dwordx4 v[234:237], v[228:229], off offset:528
	s_waitcnt vmcnt(12)
	v_lshlrev_b64 v[158:159], 1, v[158:159]
	v_pk_fma_f32 v[126:127], v[126:127], 0.5, v[166:167] op_sel_hi:[1,0,1]
	v_pk_fma_f32 v[124:125], v[124:125], 0.5, v[164:165] op_sel_hi:[1,0,1]
	v_lshl_add_u64 v[154:155], s[30:31], 0, v[160:161]
	global_store_dwordx4 v[154:155], v[124:127], off
	v_cvt_pk_bf16_f32 v156, v124, v125
	v_cvt_pk_bf16_f32 v157, v126, v127
	v_mul_f32_e32 v125, v125, v125
	v_lshl_add_u64 v[160:161], s[40:41], 0, v[158:159]
	v_fmac_f32_e32 v125, v124, v124
	v_mul_f32_e32 v124, v127, v127
	global_store_dwordx2 v[160:161], v[156:157], off
	v_fmac_f32_e32 v124, v126, v126
	v_add_f32_e32 v156, v125, v124
	v_pk_fma_f32 v[122:123], v[122:123], 0.5, v[170:171] op_sel_hi:[1,0,1]
	v_pk_fma_f32 v[120:121], v[120:121], 0.5, v[168:169] op_sel_hi:[1,0,1]
	global_store_dwordx4 v[154:155], v[120:123], off offset:16
	v_cvt_pk_bf16_f32 v124, v120, v121
	v_or_b32_e32 v126, 8, v158
	v_mul_f32_e32 v121, v121, v121
	v_mov_b32_e32 v127, v159
	v_fmac_f32_e32 v121, v120, v120
	v_mul_f32_e32 v120, v123, v123
	v_cvt_pk_bf16_f32 v125, v122, v123
	v_lshl_add_u64 v[126:127], s[40:41], 0, v[126:127]
	v_fmac_f32_e32 v120, v122, v122
	global_store_dwordx2 v[126:127], v[124:125], off
	v_add_f32_e32 v120, v121, v120
	v_add_f32_e32 v124, v156, v120
	v_pk_fma_f32 v[118:119], v[118:119], 0.5, v[174:175] op_sel_hi:[1,0,1]
	v_pk_fma_f32 v[116:117], v[116:117], 0.5, v[172:173] op_sel_hi:[1,0,1]
	global_store_dwordx4 v[154:155], v[116:119], off offset:512
	v_cvt_pk_bf16_f32 v120, v116, v117
	v_or_b32_e32 v122, 0x100, v158
	v_mul_f32_e32 v117, v117, v117
	v_mov_b32_e32 v123, v159
	v_fmac_f32_e32 v117, v116, v116
	v_mul_f32_e32 v116, v119, v119
	v_cvt_pk_bf16_f32 v121, v118, v119
	v_lshl_add_u64 v[122:123], s[40:41], 0, v[122:123]
	v_fmac_f32_e32 v116, v118, v118
	global_store_dwordx2 v[122:123], v[120:121], off
	v_add_f32_e32 v116, v117, v116
	v_add_f32_e32 v120, v124, v116
	v_or_b32_e32 v158, 0x108, v158
	v_pk_fma_f32 v[114:115], v[114:115], 0.5, v[178:179] op_sel_hi:[1,0,1]
	v_pk_fma_f32 v[112:113], v[112:113], 0.5, v[176:177] op_sel_hi:[1,0,1]
	v_mov_b32_e32 v230, 0x100000
	v_lshl_add_u64 v[228:229], v[232:233], 0, v[230:231]
	global_load_dwordx4 v[164:167], v[228:229], off
	global_load_dwordx4 v[168:171], v[228:229], off offset:16
	global_load_dwordx4 v[172:175], v[228:229], off offset:512
	global_load_dwordx4 v[176:179], v[228:229], off offset:528
	global_store_dwordx4 v[154:155], v[112:115], off offset:528
	v_cvt_pk_bf16_f32 v116, v112, v113
	v_cvt_pk_bf16_f32 v117, v114, v115
	v_mul_f32_e32 v113, v113, v113
	v_fmac_f32_e32 v113, v112, v112
	v_mul_f32_e32 v112, v115, v115
	v_fmac_f32_e32 v112, v114, v114
	v_add_f32_e32 v112, v113, v112
	v_add_f32_e32 v112, v120, v112
	v_mov_b32_e32 v113, v112
	s_nop 1
	v_permlane16_swap_b32 v112, v113
	v_lshl_add_u64 v[118:119], s[40:41], 0, v[158:159]
	v_add_f32_e32 v112, v112, v113
	v_mov_b32_e32 v113, v112
	global_store_dwordx2 v[118:119], v[116:117], off
	s_nop 1
	v_permlane32_swap_b32 v112, v113
	s_and_saveexec_b64 s[12:13], s[2:3]
	s_cbranch_execz .LBB0_425
	v_lshl_add_u64 v[114:115], v[148:149], 2, s[90:91]
	v_add_f32_e32 v112, v112, v113
	global_atomic_add_f32 v[114:115], v112, off
; __device__ __forceinline__ unsigned pk2(float lo, float hi) { f32x2_t v = {lo, hi}; bf16x2_t b = __builtin_convertvector(v, bf16x2_t); return __builtin_bit_cast(unsigned, b); }
; __device__ __forceinline__ float xor16_sum(float v) { float a = v, b = v; swap16(a, b); return a + b; }
; __device__ __forceinline__ float xor32_sum(float v) { float a = v, b = v; swap32(a, b); return a + b; }
;     __device__ __forceinline__ void operator()(const f32x4 (&acc)[2][2][4][2], const Unit& u, int wr, int wc, int fr, int fq) const {
;     ...
;         for (int ai = 0; ai < 2; ++ai)
; #pragma unroll
;             for (int m = 0; m < 4; ++m) {
;                 const int row = row0 + ai * HALF + m * 16; float sq = 0.f;
; #pragma unroll
;                 for (int bj = 0; bj < 2; ++bj)
; #pragma unroll
;                     for (int n = 0; n < 2; ++n) {
;                         const size_t idx = (size_t)row * ldc + u.pn * BM + bj * HALF + wc * 32 + 8 * fq + 4 * n;
;                         const f32x4 b = *(const f32x4*)(base + idx);
;                         const f32x4 v = b + acc[ai][bj][m][n] * alpha;
;                         *(f32x4*)(out + idx) = v;
;                         if (NORM) { u32x2 w; w.x = pk2(v[0], v[1]); w.y = pk2(v[2], v[3]); *(u32x2*)(xb + idx) = w; sq += (v[0] * v[0] + v[1] * v[1]) + (v[2] * v[2] + v[3] * v[3]); }
;                     }
;                 if (NORM) { sq = xor16_sum(sq); sq = xor32_sum(sq); if (fq == 0) __hip_atomic_fetch_add(ss + row, sq, __ATOMIC_RELAXED, __HIP_MEMORY_SCOPE_AGENT); }
.LBB0_425:
	s_or_b64 exec, exec, s[12:13]
	v_or_b32_e32 v112, 16, v148
	v_ashrrev_i32_e32 v113, 31, v112
	v_lshlrev_b64 v[114:115], 11, v[112:113]
	v_lshl_add_u64 v[118:119], v[114:115], 0, v[146:147]
	v_lshlrev_b64 v[120:121], 2, v[118:119]
	v_lshl_add_u64 v[122:123], s[52:53], 0, v[120:121]
	s_waitcnt vmcnt(20)
	v_lshlrev_b64 v[118:119], 1, v[118:119]
	v_pk_fma_f32 v[110:111], v[110:111], 0.5, v[182:183] op_sel_hi:[1,0,1]
	v_pk_fma_f32 v[108:109], v[108:109], 0.5, v[180:181] op_sel_hi:[1,0,1]
	v_lshl_add_u64 v[114:115], s[30:31], 0, v[120:121]
	global_store_dwordx4 v[114:115], v[108:111], off
	v_cvt_pk_bf16_f32 v116, v108, v109
	v_cvt_pk_bf16_f32 v117, v110, v111
	v_mul_f32_e32 v109, v109, v109
	v_lshl_add_u64 v[120:121], s[40:41], 0, v[118:119]
	v_fmac_f32_e32 v109, v108, v108
	v_mul_f32_e32 v108, v111, v111
	global_store_dwordx2 v[120:121], v[116:117], off
	v_fmac_f32_e32 v108, v110, v110
	v_add_f32_e32 v116, v109, v108
	v_pk_fma_f32 v[106:107], v[106:107], 0.5, v[190:191] op_sel_hi:[1,0,1]
	v_pk_fma_f32 v[104:105], v[104:105], 0.5, v[188:189] op_sel_hi:[1,0,1]
	global_store_dwordx4 v[114:115], v[104:107], off offset:16
	v_cvt_pk_bf16_f32 v108, v104, v105
	v_or_b32_e32 v110, 8, v118
	v_mul_f32_e32 v105, v105, v105
	v_mov_b32_e32 v111, v119
	v_fmac_f32_e32 v105, v104, v104
	v_mul_f32_e32 v104, v107, v107
	v_cvt_pk_bf16_f32 v109, v106, v107
	v_lshl_add_u64 v[110:111], s[40:41], 0, v[110:111]
	v_fmac_f32_e32 v104, v106, v106
	global_store_dwordx2 v[110:111], v[108:109], off
	v_add_f32_e32 v104, v105, v104
	v_add_f32_e32 v108, v116, v104
	v_pk_fma_f32 v[102:103], v[102:103], 0.5, v[194:195] op_sel_hi:[1,0,1]
	v_pk_fma_f32 v[100:101], v[100:101], 0.5, v[192:193] op_sel_hi:[1,0,1]
	global_store_dwordx4 v[114:115], v[100:103], off offset:512
	v_cvt_pk_bf16_f32 v104, v100, v101
	v_or_b32_e32 v106, 0x100, v118
	v_mul_f32_e32 v101, v101, v101
	v_mov_b32_e32 v107, v119
	v_fmac_f32_e32 v101, v100, v100
	v_mul_f32_e32 v100, v103, v103
	v_cvt_pk_bf16_f32 v105, v102, v103
	v_lshl_add_u64 v[106:107], s[40:41], 0, v[106:107]
	v_fmac_f32_e32 v100, v102, v102
	global_store_dwordx2 v[106:107], v[104:105], off
	v_add_f32_e32 v100, v101, v100
	v_add_f32_e32 v104, v108, v100
	v_or_b32_e32 v118, 0x108, v118
	v_pk_fma_f32 v[98:99], v[98:99], 0.5, v[198:199] op_sel_hi:[1,0,1]
	v_pk_fma_f32 v[96:97], v[96:97], 0.5, v[196:197] op_sel_hi:[1,0,1]
	v_mov_b32_e32 v230, 0x120000
	v_lshl_add_u64 v[228:229], v[232:233], 0, v[230:231]
	global_load_dwordx4 v[180:183], v[228:229], off
	global_load_dwordx4 v[188:191], v[228:229], off offset:16
	global_load_dwordx4 v[192:195], v[228:229], off offset:512
	global_load_dwordx4 v[196:199], v[228:229], off offset:528
	global_store_dwordx4 v[114:115], v[96:99], off offset:528
	v_cvt_pk_bf16_f32 v100, v96, v97
	v_cvt_pk_bf16_f32 v101, v98, v99
	v_mul_f32_e32 v97, v97, v97
	v_fmac_f32_e32 v97, v96, v96
	v_mul_f32_e32 v96, v99, v99
	v_fmac_f32_e32 v96, v98, v98
	v_add_f32_e32 v96, v97, v96
	v_add_f32_e32 v96, v104, v96
	v_mov_b32_e32 v97, v96
	s_nop 1
	v_permlane16_swap_b32 v96, v97
	v_lshl_add_u64 v[102:103], s[40:41], 0, v[118:119]
	v_add_f32_e32 v96, v96, v97
	v_mov_b32_e32 v97, v96
	global_store_dwordx2 v[102:103], v[100:101], off
	s_nop 1
	v_permlane32_swap_b32 v96, v97
	s_and_saveexec_b64 s[12:13], s[2:3]
	s_cbranch_execz .LBB0_427
	v_lshl_add_u64 v[98:99], v[112:113], 2, s[90:91]
	v_add_f32_e32 v96, v96, v97
	global_atomic_add_f32 v[98:99], v96, off
.LBB0_427:
	s_or_b64 exec, exec, s[12:13]
	v_or_b32_e32 v96, 32, v148
	v_ashrrev_i32_e32 v97, 31, v96
	v_lshlrev_b64 v[98:99], 11, v[96:97]
	v_lshl_add_u64 v[102:103], v[98:99], 0, v[146:147]
	v_lshlrev_b64 v[104:105], 2, v[102:103]
	v_lshl_add_u64 v[106:107], s[52:53], 0, v[104:105]
	s_waitcnt vmcnt(28)
	v_lshlrev_b64 v[102:103], 1, v[102:103]
	v_pk_fma_f32 v[94:95], v[94:95], 0.5, v[202:203] op_sel_hi:[1,0,1]
	v_pk_fma_f32 v[92:93], v[92:93], 0.5, v[200:201] op_sel_hi:[1,0,1]
	v_lshl_add_u64 v[98:99], s[30:31], 0, v[104:105]
	global_store_dwordx4 v[98:99], v[92:95], off
	v_cvt_pk_bf16_f32 v100, v92, v93
	v_cvt_pk_bf16_f32 v101, v94, v95
	v_mul_f32_e32 v93, v93, v93
	v_lshl_add_u64 v[104:105], s[40:41], 0, v[102:103]
	v_fmac_f32_e32 v93, v92, v92
	v_mul_f32_e32 v92, v95, v95
	global_store_dwordx2 v[104:105], v[100:101], off
	v_fmac_f32_e32 v92, v94, v94
	v_add_f32_e32 v100, v93, v92
	v_pk_fma_f32 v[90:91], v[90:91], 0.5, v[206:207] op_sel_hi:[1,0,1]
	v_pk_fma_f32 v[88:89], v[88:89], 0.5, v[204:205] op_sel_hi:[1,0,1]
	global_store_dwordx4 v[98:99], v[88:91], off offset:16
	v_cvt_pk_bf16_f32 v92, v88, v89
	v_or_b32_e32 v94, 8, v102
	v_mul_f32_e32 v89, v89, v89
	v_mov_b32_e32 v95, v103
	v_fmac_f32_e32 v89, v88, v88
	v_mul_f32_e32 v88, v91, v91
	v_cvt_pk_bf16_f32 v93, v90, v91
	v_lshl_add_u64 v[94:95], s[40:41], 0, v[94:95]
	v_fmac_f32_e32 v88, v90, v90
	global_store_dwordx2 v[94:95], v[92:93], off
	v_add_f32_e32 v88, v89, v88
	v_add_f32_e32 v92, v100, v88
	v_pk_fma_f32 v[86:87], v[86:87], 0.5, v[210:211] op_sel_hi:[1,0,1]
	v_pk_fma_f32 v[84:85], v[84:85], 0.5, v[208:209] op_sel_hi:[1,0,1]
	global_store_dwordx4 v[98:99], v[84:87], off offset:512
	v_cvt_pk_bf16_f32 v88, v84, v85
	v_or_b32_e32 v90, 0x100, v102
	v_mul_f32_e32 v85, v85, v85
	v_mov_b32_e32 v91, v103
	v_fmac_f32_e32 v85, v84, v84
	v_mul_f32_e32 v84, v87, v87
	v_cvt_pk_bf16_f32 v89, v86, v87
	v_lshl_add_u64 v[90:91], s[40:41], 0, v[90:91]
	v_fmac_f32_e32 v84, v86, v86
	global_store_dwordx2 v[90:91], v[88:89], off
	v_add_f32_e32 v84, v85, v84
	v_add_f32_e32 v88, v92, v84
	v_or_b32_e32 v102, 0x108, v102
	v_pk_fma_f32 v[82:83], v[82:83], 0.5, v[214:215] op_sel_hi:[1,0,1]
	v_pk_fma_f32 v[80:81], v[80:81], 0.5, v[212:213] op_sel_hi:[1,0,1]
	v_mov_b32_e32 v230, 0x140000
	v_lshl_add_u64 v[228:229], v[232:233], 0, v[230:231]
	global_load_dwordx4 v[200:203], v[228:229], off
	global_load_dwordx4 v[204:207], v[228:229], off offset:16
	global_load_dwordx4 v[208:211], v[228:229], off offset:512
	global_load_dwordx4 v[212:215], v[228:229], off offset:528
	global_store_dwordx4 v[98:99], v[80:83], off offset:528
	v_cvt_pk_bf16_f32 v84, v80, v81
	v_cvt_pk_bf16_f32 v85, v82, v83
	v_mul_f32_e32 v81, v81, v81
	v_fmac_f32_e32 v81, v80, v80
	v_mul_f32_e32 v80, v83, v83
	v_fmac_f32_e32 v80, v82, v82
	v_add_f32_e32 v80, v81, v80
	v_add_f32_e32 v80, v88, v80
	v_mov_b32_e32 v81, v80
	s_nop 1
	v_permlane16_swap_b32 v80, v81
	v_lshl_add_u64 v[86:87], s[40:41], 0, v[102:103]
	v_add_f32_e32 v80, v80, v81
	v_mov_b32_e32 v81, v80
	global_store_dwordx2 v[86:87], v[84:85], off
	s_nop 1
	v_permlane32_swap_b32 v80, v81
	s_and_saveexec_b64 s[12:13], s[2:3]
	s_cbranch_execz .LBB0_429
	v_lshl_add_u64 v[82:83], v[96:97], 2, s[90:91]
	v_add_f32_e32 v80, v80, v81
	global_atomic_add_f32 v[82:83], v80, off
; __device__ __forceinline__ unsigned pk2(float lo, float hi) { f32x2_t v = {lo, hi}; bf16x2_t b = __builtin_convertvector(v, bf16x2_t); return __builtin_bit_cast(unsigned, b); }
; __device__ __forceinline__ float xor16_sum(float v) { float a = v, b = v; swap16(a, b); return a + b; }
; __device__ __forceinline__ float xor32_sum(float v) { float a = v, b = v; swap32(a, b); return a + b; }
;     __device__ __forceinline__ void operator()(const f32x4 (&acc)[2][2][4][2], const Unit& u, int wr, int wc, int fr, int fq) const {
;     ...
;         for (int ai = 0; ai < 2; ++ai)
; #pragma unroll
;             for (int m = 0; m < 4; ++m) {
;                 const int row = row0 + ai * HALF + m * 16; float sq = 0.f;
; #pragma unroll
;                 for (int bj = 0; bj < 2; ++bj)
; #pragma unroll
;                     for (int n = 0; n < 2; ++n) {
;                         const size_t idx = (size_t)row * ldc + u.pn * BM + bj * HALF + wc * 32 + 8 * fq + 4 * n;
;                         const f32x4 b = *(const f32x4*)(base + idx);
;                         const f32x4 v = b + acc[ai][bj][m][n] * alpha;
;                         *(f32x4*)(out + idx) = v;
;                         if (NORM) { u32x2 w; w.x = pk2(v[0], v[1]); w.y = pk2(v[2], v[3]); *(u32x2*)(xb + idx) = w; sq += (v[0] * v[0] + v[1] * v[1]) + (v[2] * v[2] + v[3] * v[3]); }
;                     }
;                 if (NORM) { sq = xor16_sum(sq); sq = xor32_sum(sq); if (fq == 0) __hip_atomic_fetch_add(ss + row, sq, __ATOMIC_RELAXED, __HIP_MEMORY_SCOPE_AGENT); }
.LBB0_429:
	s_or_b64 exec, exec, s[12:13]
	v_or_b32_e32 v80, 48, v148
	v_ashrrev_i32_e32 v81, 31, v80
	v_lshlrev_b64 v[82:83], 11, v[80:81]
	v_lshl_add_u64 v[86:87], v[82:83], 0, v[146:147]
	v_lshlrev_b64 v[88:89], 2, v[86:87]
	v_lshl_add_u64 v[90:91], s[52:53], 0, v[88:89]
	s_waitcnt vmcnt(36)
	v_lshlrev_b64 v[86:87], 1, v[86:87]
	v_pk_fma_f32 v[78:79], v[78:79], 0.5, v[218:219] op_sel_hi:[1,0,1]
	v_pk_fma_f32 v[76:77], v[76:77], 0.5, v[216:217] op_sel_hi:[1,0,1]
	v_lshl_add_u64 v[82:83], s[30:31], 0, v[88:89]
	global_store_dwordx4 v[82:83], v[76:79], off
	v_cvt_pk_bf16_f32 v84, v76, v77
	v_cvt_pk_bf16_f32 v85, v78, v79
	v_mul_f32_e32 v77, v77, v77
	v_lshl_add_u64 v[88:89], s[40:41], 0, v[86:87]
	v_fmac_f32_e32 v77, v76, v76
	v_mul_f32_e32 v76, v79, v79
	global_store_dwordx2 v[88:89], v[84:85], off
	v_fmac_f32_e32 v76, v78, v78
	v_add_f32_e32 v84, v77, v76
	v_pk_fma_f32 v[74:75], v[74:75], 0.5, v[222:223] op_sel_hi:[1,0,1]
	v_pk_fma_f32 v[72:73], v[72:73], 0.5, v[220:221] op_sel_hi:[1,0,1]
	global_store_dwordx4 v[82:83], v[72:75], off offset:16
	v_cvt_pk_bf16_f32 v76, v72, v73
	v_or_b32_e32 v78, 8, v86
	v_mul_f32_e32 v73, v73, v73
	v_mov_b32_e32 v79, v87
	v_fmac_f32_e32 v73, v72, v72
	v_mul_f32_e32 v72, v75, v75
	v_cvt_pk_bf16_f32 v77, v74, v75
	v_lshl_add_u64 v[78:79], s[40:41], 0, v[78:79]
	v_fmac_f32_e32 v72, v74, v74
	global_store_dwordx2 v[78:79], v[76:77], off
	v_add_f32_e32 v72, v73, v72
	v_add_f32_e32 v76, v84, v72
	v_pk_fma_f32 v[70:71], v[70:71], 0.5, v[226:227] op_sel_hi:[1,0,1]
	v_pk_fma_f32 v[68:69], v[68:69], 0.5, v[224:225] op_sel_hi:[1,0,1]
	global_store_dwordx4 v[82:83], v[68:71], off offset:512
	v_cvt_pk_bf16_f32 v72, v68, v69
	v_or_b32_e32 v74, 0x100, v86
	v_mul_f32_e32 v69, v69, v69
	v_mov_b32_e32 v75, v87
	v_fmac_f32_e32 v69, v68, v68
	v_mul_f32_e32 v68, v71, v71
	v_cvt_pk_bf16_f32 v73, v70, v71
	v_lshl_add_u64 v[74:75], s[40:41], 0, v[74:75]
	v_fmac_f32_e32 v68, v70, v70
	global_store_dwordx2 v[74:75], v[72:73], off
	v_add_f32_e32 v68, v69, v68
	v_add_f32_e32 v72, v76, v68
	v_or_b32_e32 v86, 0x108, v86
	v_pk_fma_f32 v[66:67], v[66:67], 0.5, v[236:237] op_sel_hi:[1,0,1]
	v_pk_fma_f32 v[64:65], v[64:65], 0.5, v[234:235] op_sel_hi:[1,0,1]
	v_mov_b32_e32 v230, 0x160000
	v_lshl_add_u64 v[228:229], v[232:233], 0, v[230:231]
	global_load_dwordx4 v[216:219], v[228:229], off
	global_load_dwordx4 v[220:223], v[228:229], off offset:16
	global_load_dwordx4 v[224:227], v[228:229], off offset:512
	global_load_dwordx4 v[234:237], v[228:229], off offset:528
	global_store_dwordx4 v[82:83], v[64:67], off offset:528
	v_cvt_pk_bf16_f32 v68, v64, v65
	v_cvt_pk_bf16_f32 v69, v66, v67
	v_mul_f32_e32 v65, v65, v65
	v_fmac_f32_e32 v65, v64, v64
	v_mul_f32_e32 v64, v67, v67
	v_fmac_f32_e32 v64, v66, v66
	v_add_f32_e32 v64, v65, v64
	v_add_f32_e32 v64, v72, v64
	v_mov_b32_e32 v65, v64
	s_nop 1
	v_permlane16_swap_b32 v64, v65
	v_lshl_add_u64 v[70:71], s[40:41], 0, v[86:87]
	v_add_f32_e32 v64, v64, v65
	v_mov_b32_e32 v65, v64
	global_store_dwordx2 v[70:71], v[68:69], off
	s_nop 1
	v_permlane32_swap_b32 v64, v65
	s_and_saveexec_b64 s[12:13], s[2:3]
	s_cbranch_execz .LBB0_431
	v_lshl_add_u64 v[66:67], v[80:81], 2, s[90:91]
	v_add_f32_e32 v64, v64, v65
	global_atomic_add_f32 v[66:67], v64, off
.LBB0_431:
	s_or_b64 exec, exec, s[12:13]
	v_add_u32_e32 v64, 0x80, v148
	v_ashrrev_i32_e32 v65, 31, v64
	v_lshlrev_b64 v[66:67], 11, v[64:65]
	v_lshl_add_u64 v[70:71], v[66:67], 0, v[146:147]
	v_lshlrev_b64 v[72:73], 2, v[70:71]
	v_lshl_add_u64 v[74:75], s[52:53], 0, v[72:73]
	s_waitcnt vmcnt(36)
	v_lshlrev_b64 v[70:71], 1, v[70:71]
	v_pk_fma_f32 v[62:63], v[62:63], 0.5, v[166:167] op_sel_hi:[1,0,1]
	v_pk_fma_f32 v[60:61], v[60:61], 0.5, v[164:165] op_sel_hi:[1,0,1]
	v_lshl_add_u64 v[66:67], s[30:31], 0, v[72:73]
	global_store_dwordx4 v[66:67], v[60:63], off
	v_cvt_pk_bf16_f32 v68, v60, v61
	v_cvt_pk_bf16_f32 v69, v62, v63
	v_mul_f32_e32 v61, v61, v61
	v_lshl_add_u64 v[72:73], s[40:41], 0, v[70:71]
	v_fmac_f32_e32 v61, v60, v60
	v_mul_f32_e32 v60, v63, v63
	global_store_dwordx2 v[72:73], v[68:69], off
	v_fmac_f32_e32 v60, v62, v62
	v_add_f32_e32 v68, v61, v60
	v_pk_fma_f32 v[58:59], v[58:59], 0.5, v[170:171] op_sel_hi:[1,0,1]
	v_pk_fma_f32 v[56:57], v[56:57], 0.5, v[168:169] op_sel_hi:[1,0,1]
	global_store_dwordx4 v[66:67], v[56:59], off offset:16
	v_cvt_pk_bf16_f32 v60, v56, v57
	v_or_b32_e32 v62, 8, v70
	v_mul_f32_e32 v57, v57, v57
	v_mov_b32_e32 v63, v71
	v_fmac_f32_e32 v57, v56, v56
	v_mul_f32_e32 v56, v59, v59
	v_cvt_pk_bf16_f32 v61, v58, v59
	v_lshl_add_u64 v[62:63], s[40:41], 0, v[62:63]
	v_fmac_f32_e32 v56, v58, v58
	global_store_dwordx2 v[62:63], v[60:61], off
	v_add_f32_e32 v56, v57, v56
	v_add_f32_e32 v60, v68, v56
	v_pk_fma_f32 v[54:55], v[54:55], 0.5, v[174:175] op_sel_hi:[1,0,1]
	v_pk_fma_f32 v[52:53], v[52:53], 0.5, v[172:173] op_sel_hi:[1,0,1]
	global_store_dwordx4 v[66:67], v[52:55], off offset:512
	v_cvt_pk_bf16_f32 v56, v52, v53
	v_or_b32_e32 v58, 0x100, v70
	v_mul_f32_e32 v53, v53, v53
	v_mov_b32_e32 v59, v71
	v_fmac_f32_e32 v53, v52, v52
	v_mul_f32_e32 v52, v55, v55
	v_cvt_pk_bf16_f32 v57, v54, v55
	v_lshl_add_u64 v[58:59], s[40:41], 0, v[58:59]
	v_fmac_f32_e32 v52, v54, v54
	global_store_dwordx2 v[58:59], v[56:57], off
	v_add_f32_e32 v52, v53, v52
	v_add_f32_e32 v56, v60, v52
	v_or_b32_e32 v70, 0x108, v70
	v_pk_fma_f32 v[50:51], v[50:51], 0.5, v[178:179] op_sel_hi:[1,0,1]
	v_pk_fma_f32 v[48:49], v[48:49], 0.5, v[176:177] op_sel_hi:[1,0,1]
	global_store_dwordx4 v[66:67], v[48:51], off offset:528
	v_cvt_pk_bf16_f32 v52, v48, v49
	v_cvt_pk_bf16_f32 v53, v50, v51
	v_mul_f32_e32 v49, v49, v49
	v_fmac_f32_e32 v49, v48, v48
	v_mul_f32_e32 v48, v51, v51
	v_fmac_f32_e32 v48, v50, v50
	v_add_f32_e32 v48, v49, v48
	v_add_f32_e32 v48, v56, v48
	v_mov_b32_e32 v49, v48
	s_nop 1
	v_permlane16_swap_b32 v49, v48
	v_lshl_add_u64 v[54:55], s[40:41], 0, v[70:71]
	v_add_f32_e32 v48, v49, v48
	v_mov_b32_e32 v49, v48
	global_store_dwordx2 v[54:55], v[52:53], off
	s_nop 1
	v_permlane32_swap_b32 v49, v48
	s_and_saveexec_b64 s[12:13], s[2:3]
	s_cbranch_execz .LBB0_433
	v_lshl_add_u64 v[50:51], v[64:65], 2, s[90:91]
	v_add_f32_e32 v48, v49, v48
	global_atomic_add_f32 v[50:51], v48, off
; __device__ __forceinline__ unsigned pk2(float lo, float hi) { f32x2_t v = {lo, hi}; bf16x2_t b = __builtin_convertvector(v, bf16x2_t); return __builtin_bit_cast(unsigned, b); }
; __device__ __forceinline__ float xor16_sum(float v) { float a = v, b = v; swap16(a, b); return a + b; }
; __device__ __forceinline__ float xor32_sum(float v) { float a = v, b = v; swap32(a, b); return a + b; }
;     __device__ __forceinline__ void operator()(const f32x4 (&acc)[2][2][4][2], const Unit& u, int wr, int wc, int fr, int fq) const {
;     ...
;         for (int ai = 0; ai < 2; ++ai)
; #pragma unroll
;             for (int m = 0; m < 4; ++m) {
;                 const int row = row0 + ai * HALF + m * 16; float sq = 0.f;
; #pragma unroll
;                 for (int bj = 0; bj < 2; ++bj)
; #pragma unroll
;                     for (int n = 0; n < 2; ++n) {
;                         const size_t idx = (size_t)row * ldc + u.pn * BM + bj * HALF + wc * 32 + 8 * fq + 4 * n;
;                         const f32x4 b = *(const f32x4*)(base + idx);
;                         const f32x4 v = b + acc[ai][bj][m][n] * alpha;
;                         *(f32x4*)(out + idx) = v;
;                         if (NORM) { u32x2 w; w.x = pk2(v[0], v[1]); w.y = pk2(v[2], v[3]); *(u32x2*)(xb + idx) = w; sq += (v[0] * v[0] + v[1] * v[1]) + (v[2] * v[2] + v[3] * v[3]); }
;                     }
;                 if (NORM) { sq = xor16_sum(sq); sq = xor32_sum(sq); if (fq == 0) __hip_atomic_fetch_add(ss + row, sq, __ATOMIC_RELAXED, __HIP_MEMORY_SCOPE_AGENT); }
.LBB0_433:
	s_or_b64 exec, exec, s[12:13]
	v_add_u32_e32 v48, 0x90, v148
	v_ashrrev_i32_e32 v49, 31, v48
	v_lshlrev_b64 v[50:51], 11, v[48:49]
	v_lshl_add_u64 v[54:55], v[50:51], 0, v[146:147]
	v_lshlrev_b64 v[56:57], 2, v[54:55]
	v_lshl_add_u64 v[58:59], s[52:53], 0, v[56:57]
	s_waitcnt vmcnt(32)
	v_lshlrev_b64 v[54:55], 1, v[54:55]
	v_pk_fma_f32 v[46:47], v[46:47], 0.5, v[182:183] op_sel_hi:[1,0,1]
	v_pk_fma_f32 v[44:45], v[44:45], 0.5, v[180:181] op_sel_hi:[1,0,1]
	v_lshl_add_u64 v[50:51], s[30:31], 0, v[56:57]
	global_store_dwordx4 v[50:51], v[44:47], off
	v_cvt_pk_bf16_f32 v52, v44, v45
	v_cvt_pk_bf16_f32 v53, v46, v47
	v_mul_f32_e32 v45, v45, v45
	v_lshl_add_u64 v[56:57], s[40:41], 0, v[54:55]
	v_fmac_f32_e32 v45, v44, v44
	v_mul_f32_e32 v44, v47, v47
	global_store_dwordx2 v[56:57], v[52:53], off
	v_fmac_f32_e32 v44, v46, v46
	v_add_f32_e32 v52, v45, v44
	v_pk_fma_f32 v[42:43], v[42:43], 0.5, v[190:191] op_sel_hi:[1,0,1]
	v_pk_fma_f32 v[40:41], v[40:41], 0.5, v[188:189] op_sel_hi:[1,0,1]
	global_store_dwordx4 v[50:51], v[40:43], off offset:16
	v_cvt_pk_bf16_f32 v44, v40, v41
	v_or_b32_e32 v46, 8, v54
	v_mul_f32_e32 v41, v41, v41
	v_mov_b32_e32 v47, v55
	v_fmac_f32_e32 v41, v40, v40
	v_mul_f32_e32 v40, v43, v43
	v_cvt_pk_bf16_f32 v45, v42, v43
	v_lshl_add_u64 v[46:47], s[40:41], 0, v[46:47]
	v_fmac_f32_e32 v40, v42, v42
	global_store_dwordx2 v[46:47], v[44:45], off
	v_add_f32_e32 v40, v41, v40
	v_add_f32_e32 v44, v52, v40
	v_pk_fma_f32 v[38:39], v[38:39], 0.5, v[194:195] op_sel_hi:[1,0,1]
	v_pk_fma_f32 v[36:37], v[36:37], 0.5, v[192:193] op_sel_hi:[1,0,1]
	global_store_dwordx4 v[50:51], v[36:39], off offset:512
	v_cvt_pk_bf16_f32 v40, v36, v37
	v_or_b32_e32 v42, 0x100, v54
	v_mul_f32_e32 v37, v37, v37
	v_mov_b32_e32 v43, v55
	v_fmac_f32_e32 v37, v36, v36
	v_mul_f32_e32 v36, v39, v39
	v_cvt_pk_bf16_f32 v41, v38, v39
	v_lshl_add_u64 v[42:43], s[40:41], 0, v[42:43]
	v_fmac_f32_e32 v36, v38, v38
	global_store_dwordx2 v[42:43], v[40:41], off
	v_add_f32_e32 v36, v37, v36
	v_add_f32_e32 v40, v44, v36
	v_or_b32_e32 v54, 0x108, v54
	v_pk_fma_f32 v[34:35], v[34:35], 0.5, v[198:199] op_sel_hi:[1,0,1]
	v_pk_fma_f32 v[32:33], v[32:33], 0.5, v[196:197] op_sel_hi:[1,0,1]
	global_store_dwordx4 v[50:51], v[32:35], off offset:528
	v_cvt_pk_bf16_f32 v36, v32, v33
	v_cvt_pk_bf16_f32 v37, v34, v35
	v_mul_f32_e32 v33, v33, v33
	v_fmac_f32_e32 v33, v32, v32
	v_mul_f32_e32 v32, v35, v35
	v_fmac_f32_e32 v32, v34, v34
	v_add_f32_e32 v32, v33, v32
	v_add_f32_e32 v32, v40, v32
	v_mov_b32_e32 v33, v32
	s_nop 1
	v_permlane16_swap_b32 v32, v33
	v_lshl_add_u64 v[38:39], s[40:41], 0, v[54:55]
	v_add_f32_e32 v32, v32, v33
	v_mov_b32_e32 v33, v32
	global_store_dwordx2 v[38:39], v[36:37], off
	s_nop 1
	v_permlane32_swap_b32 v32, v33
	s_and_saveexec_b64 s[12:13], s[2:3]
	s_cbranch_execz .LBB0_435
	v_lshl_add_u64 v[34:35], v[48:49], 2, s[90:91]
	v_add_f32_e32 v32, v32, v33
	global_atomic_add_f32 v[34:35], v32, off
; __device__ __forceinline__ unsigned pk2(float lo, float hi) { f32x2_t v = {lo, hi}; bf16x2_t b = __builtin_convertvector(v, bf16x2_t); return __builtin_bit_cast(unsigned, b); }
; __device__ __forceinline__ float xor16_sum(float v) { float a = v, b = v; swap16(a, b); return a + b; }
; __device__ __forceinline__ float xor32_sum(float v) { float a = v, b = v; swap32(a, b); return a + b; }
;     __device__ __forceinline__ void operator()(const f32x4 (&acc)[2][2][4][2], const Unit& u, int wr, int wc, int fr, int fq) const {
;     ...
;                 const int row = row0 + ai * HALF + m * 16; float sq = 0.f;
; #pragma unroll
;                 for (int bj = 0; bj < 2; ++bj)
; #pragma unroll
;                     for (int n = 0; n < 2; ++n) {
;                         const size_t idx = (size_t)row * ldc + u.pn * BM + bj * HALF + wc * 32 + 8 * fq + 4 * n;
;                         const f32x4 b = *(const f32x4*)(base + idx);
;                         const f32x4 v = b + acc[ai][bj][m][n] * alpha;
;                         *(f32x4*)(out + idx) = v;
;                         if (NORM) { u32x2 w; w.x = pk2(v[0], v[1]); w.y = pk2(v[2], v[3]); *(u32x2*)(xb + idx) = w; sq += (v[0] * v[0] + v[1] * v[1]) + (v[2] * v[2] + v[3] * v[3]); }
;                     }
;                 if (NORM) { sq = xor16_sum(sq); sq = xor32_sum(sq); if (fq == 0) __hip_atomic_fetch_add(ss + row, sq, __ATOMIC_RELAXED, __HIP_MEMORY_SCOPE_AGENT); }
.LBB0_435:
	s_or_b64 exec, exec, s[12:13]
	v_add_u32_e32 v32, 0xa0, v148
	v_ashrrev_i32_e32 v33, 31, v32
	v_lshlrev_b64 v[34:35], 11, v[32:33]
	v_lshl_add_u64 v[38:39], v[34:35], 0, v[146:147]
	v_lshlrev_b64 v[40:41], 2, v[38:39]
	v_lshl_add_u64 v[42:43], s[52:53], 0, v[40:41]
	s_waitcnt vmcnt(28)
	v_lshlrev_b64 v[38:39], 1, v[38:39]
	v_pk_fma_f32 v[30:31], v[30:31], 0.5, v[202:203] op_sel_hi:[1,0,1]
	v_pk_fma_f32 v[28:29], v[28:29], 0.5, v[200:201] op_sel_hi:[1,0,1]
	v_lshl_add_u64 v[34:35], s[30:31], 0, v[40:41]
	global_store_dwordx4 v[34:35], v[28:31], off
	v_cvt_pk_bf16_f32 v36, v28, v29
	v_cvt_pk_bf16_f32 v37, v30, v31
	v_mul_f32_e32 v29, v29, v29
	v_lshl_add_u64 v[40:41], s[40:41], 0, v[38:39]
	v_fmac_f32_e32 v29, v28, v28
	v_mul_f32_e32 v28, v31, v31
	global_store_dwordx2 v[40:41], v[36:37], off
	v_fmac_f32_e32 v28, v30, v30
	v_add_f32_e32 v36, v29, v28
	v_pk_fma_f32 v[26:27], v[26:27], 0.5, v[206:207] op_sel_hi:[1,0,1]
	v_pk_fma_f32 v[24:25], v[24:25], 0.5, v[204:205] op_sel_hi:[1,0,1]
	global_store_dwordx4 v[34:35], v[24:27], off offset:16
	v_cvt_pk_bf16_f32 v28, v24, v25
	v_or_b32_e32 v30, 8, v38
	v_mul_f32_e32 v25, v25, v25
	v_mov_b32_e32 v31, v39
	v_fmac_f32_e32 v25, v24, v24
	v_mul_f32_e32 v24, v27, v27
	v_cvt_pk_bf16_f32 v29, v26, v27
	v_lshl_add_u64 v[30:31], s[40:41], 0, v[30:31]
	v_fmac_f32_e32 v24, v26, v26
	global_store_dwordx2 v[30:31], v[28:29], off
	v_add_f32_e32 v24, v25, v24
	v_add_f32_e32 v28, v36, v24
	v_pk_fma_f32 v[22:23], v[22:23], 0.5, v[210:211] op_sel_hi:[1,0,1]
	v_pk_fma_f32 v[20:21], v[20:21], 0.5, v[208:209] op_sel_hi:[1,0,1]
	global_store_dwordx4 v[34:35], v[20:23], off offset:512
	v_cvt_pk_bf16_f32 v24, v20, v21
	v_or_b32_e32 v26, 0x100, v38
	v_mul_f32_e32 v21, v21, v21
	v_mov_b32_e32 v27, v39
	v_fmac_f32_e32 v21, v20, v20
	v_mul_f32_e32 v20, v23, v23
	v_cvt_pk_bf16_f32 v25, v22, v23
	v_lshl_add_u64 v[26:27], s[40:41], 0, v[26:27]
	v_fmac_f32_e32 v20, v22, v22
	global_store_dwordx2 v[26:27], v[24:25], off
	v_add_f32_e32 v20, v21, v20
	v_add_f32_e32 v24, v28, v20
	v_or_b32_e32 v38, 0x108, v38
	v_pk_fma_f32 v[18:19], v[18:19], 0.5, v[214:215] op_sel_hi:[1,0,1]
	v_pk_fma_f32 v[16:17], v[16:17], 0.5, v[212:213] op_sel_hi:[1,0,1]
	global_store_dwordx4 v[34:35], v[16:19], off offset:528
	v_cvt_pk_bf16_f32 v20, v16, v17
	v_cvt_pk_bf16_f32 v21, v18, v19
	v_mul_f32_e32 v17, v17, v17
	v_fmac_f32_e32 v17, v16, v16
	v_mul_f32_e32 v16, v19, v19
	v_fmac_f32_e32 v16, v18, v18
	v_add_f32_e32 v16, v17, v16
	v_add_f32_e32 v16, v24, v16
	v_mov_b32_e32 v17, v16
	s_nop 1
	v_permlane16_swap_b32 v16, v17
	v_lshl_add_u64 v[22:23], s[40:41], 0, v[38:39]
	v_add_f32_e32 v16, v16, v17
	v_mov_b32_e32 v17, v16
	global_store_dwordx2 v[22:23], v[20:21], off
	s_nop 1
	v_permlane32_swap_b32 v16, v17
	s_and_saveexec_b64 s[12:13], s[2:3]
	s_cbranch_execz .LBB0_437
	v_lshl_add_u64 v[18:19], v[32:33], 2, s[90:91]
	v_add_f32_e32 v16, v16, v17
	global_atomic_add_f32 v[18:19], v16, off
.LBB0_437:
	s_or_b64 exec, exec, s[12:13]
	v_add_u32_e32 v16, 0xb0, v148
	v_ashrrev_i32_e32 v17, 31, v16
	v_lshlrev_b64 v[18:19], 11, v[16:17]
	v_lshl_add_u64 v[22:23], v[18:19], 0, v[146:147]
	v_lshlrev_b64 v[24:25], 2, v[22:23]
	v_lshl_add_u64 v[26:27], s[52:53], 0, v[24:25]
	s_waitcnt vmcnt(24)
	v_lshlrev_b64 v[22:23], 1, v[22:23]
	v_pk_fma_f32 v[14:15], v[14:15], 0.5, v[218:219] op_sel_hi:[1,0,1]
	v_pk_fma_f32 v[12:13], v[12:13], 0.5, v[216:217] op_sel_hi:[1,0,1]
	v_lshl_add_u64 v[18:19], s[30:31], 0, v[24:25]
	global_store_dwordx4 v[18:19], v[12:15], off
	v_cvt_pk_bf16_f32 v20, v12, v13
	v_cvt_pk_bf16_f32 v21, v14, v15
	v_mul_f32_e32 v13, v13, v13
	v_lshl_add_u64 v[24:25], s[40:41], 0, v[22:23]
	v_fmac_f32_e32 v13, v12, v12
	v_mul_f32_e32 v12, v15, v15
	global_store_dwordx2 v[24:25], v[20:21], off
	v_fmac_f32_e32 v12, v14, v14
	v_add_f32_e32 v20, v13, v12
	v_pk_fma_f32 v[10:11], v[10:11], 0.5, v[222:223] op_sel_hi:[1,0,1]
	v_pk_fma_f32 v[8:9], v[8:9], 0.5, v[220:221] op_sel_hi:[1,0,1]
	global_store_dwordx4 v[18:19], v[8:11], off offset:16
	v_cvt_pk_bf16_f32 v12, v8, v9
	v_or_b32_e32 v14, 8, v22
	v_mul_f32_e32 v9, v9, v9
	v_mov_b32_e32 v15, v23
	v_fmac_f32_e32 v9, v8, v8
	v_mul_f32_e32 v8, v11, v11
	v_cvt_pk_bf16_f32 v13, v10, v11
	v_lshl_add_u64 v[14:15], s[40:41], 0, v[14:15]
	v_fmac_f32_e32 v8, v10, v10
	global_store_dwordx2 v[14:15], v[12:13], off
	v_add_f32_e32 v8, v9, v8
	v_add_f32_e32 v12, v20, v8
	v_pk_fma_f32 v[6:7], v[6:7], 0.5, v[226:227] op_sel_hi:[1,0,1]
	v_pk_fma_f32 v[4:5], v[4:5], 0.5, v[224:225] op_sel_hi:[1,0,1]
	global_store_dwordx4 v[18:19], v[4:7], off offset:512
	v_cvt_pk_bf16_f32 v8, v4, v5
	v_or_b32_e32 v10, 0x100, v22
	v_mul_f32_e32 v5, v5, v5
	v_mov_b32_e32 v11, v23
	v_fmac_f32_e32 v5, v4, v4
	v_mul_f32_e32 v4, v7, v7
	v_cvt_pk_bf16_f32 v9, v6, v7
	v_lshl_add_u64 v[10:11], s[40:41], 0, v[10:11]
	v_fmac_f32_e32 v4, v6, v6
	global_store_dwordx2 v[10:11], v[8:9], off
	v_add_f32_e32 v4, v5, v4
	v_add_f32_e32 v8, v12, v4
	v_or_b32_e32 v22, 0x108, v22
	v_pk_fma_f32 v[2:3], v[2:3], 0.5, v[236:237] op_sel_hi:[1,0,1]
	v_pk_fma_f32 v[0:1], v[0:1], 0.5, v[234:235] op_sel_hi:[1,0,1]
	global_store_dwordx4 v[18:19], v[0:3], off offset:528
	v_cvt_pk_bf16_f32 v4, v0, v1
	v_cvt_pk_bf16_f32 v5, v2, v3
	v_mul_f32_e32 v1, v1, v1
	v_fmac_f32_e32 v1, v0, v0
	v_mul_f32_e32 v0, v3, v3
	v_fmac_f32_e32 v0, v2, v2
	v_add_f32_e32 v0, v1, v0
	v_add_f32_e32 v0, v8, v0
	v_mov_b32_e32 v1, v0
	s_nop 1
	v_permlane16_swap_b32 v0, v1
	v_lshl_add_u64 v[6:7], s[40:41], 0, v[22:23]
	v_add_f32_e32 v0, v0, v1
	v_mov_b32_e32 v1, v0
	global_store_dwordx2 v[6:7], v[4:5], off
	s_nop 1
	v_permlane32_swap_b32 v0, v1
	s_and_saveexec_b64 s[12:13], s[2:3]
	s_cbranch_execz .LBB0_439
	v_lshl_add_u64 v[2:3], v[16:17], 2, s[90:91]
	v_add_f32_e32 v0, v0, v1
	global_atomic_add_f32 v[2:3], v0, off
